# FFN-up K loop: LDS-DMA staging rebalanced from 2/6/2/6 to 4/4/4/4 loads per segment (SA(1,0) staged in seg1, SA(0,0) in seg3; waits 8/6/8/6)
# speedup vs baseline: 1.0801x; 1.0040x over previous
.LBB0_740:
	s_add_u32 s18, s66, 0x80
	s_addc_u32 s19, s67, 0
	s_add_u32 s66, s66, 0x100
	s_addc_u32 s67, s67, 0
	s_cmp_eq_u32 s85, 12
	s_cselect_b32 s42, s81, s66
	s_cselect_b32 s43, s59, s67
	s_cselect_b32 s45, s31, s84
	s_cselect_b32 s44, s82, s83
	s_add_u32 s38, s42, 0x80
	s_addc_u32 s39, s43, 0
	s_add_u32 s68, s44, 0x80
	s_addc_u32 s69, s45, 0
	s_add_i32 s35, 0, 0x10000
	s_add_i32 s49, 0, 0x14000
	v_add_u32_e32 v96, s35, v151
	v_add_u32_e32 v150, s49, v151
	ds_read_b128 v[138:141], v96
	ds_read_b128 v[142:145], v96 offset:1024
	ds_read_b128 v[146:149], v96 offset:2048
	ds_read_b128 v[156:159], v96 offset:3072
	ds_read_b128 v[160:163], v150
	ds_read_b128 v[164:167], v150 offset:1024
	ds_read_b128 v[168:171], v150 offset:2048
	ds_read_b128 v[172:175], v150 offset:3072
	s_mov_b32 m0, s77
	ds_read_b128 v[176:179], v155
	ds_read_b128 v[180:183], v155 offset:1024
	ds_read_b128 v[190:193], v155 offset:2048
	ds_read_b128 v[194:197], v155 offset:3072
	ds_read_b128 v[198:201], v155 offset:4096
	ds_read_b128 v[202:205], v155 offset:5120
	ds_read_b128 v[206:209], v155 offset:6144
	ds_read_b128 v[210:213], v155 offset:7168
	global_load_lds_dwordx4 v136, s[18:19]
	s_mov_b32 m0, s78
	s_nop 0
	global_load_lds_dwordx4 v132, s[18:19]
	s_add_u32 s18, s18, 0x40000
	s_addc_u32 s19, s19, 0
	s_add_i32 m0, s65, 0xc000
	s_nop 0
	global_load_lds_dwordx4 v136, s[18:19]
	s_add_i32 m0, s65, 0xe000
	s_nop 0
	global_load_lds_dwordx4 v132, s[18:19]
	s_waitcnt vmcnt(8)
	s_waitcnt lgkmcnt(0)
	s_barrier
	s_setprio 1
	s_waitcnt lgkmcnt(0)
	v_mfma_f32_16x16x32_bf16 v[126:129], v[138:141], v[176:179], v[126:129]
	v_mfma_f32_16x16x32_bf16 v[118:121], v[146:149], v[176:179], v[118:121]
	v_mfma_f32_16x16x32_bf16 v[110:113], v[138:141], v[190:193], v[110:113]
	v_mfma_f32_16x16x32_bf16 v[102:105], v[146:149], v[190:193], v[102:105]
	v_mfma_f32_16x16x32_bf16 v[92:95], v[138:141], v[198:201], v[92:95]
	v_mfma_f32_16x16x32_bf16 v[84:87], v[146:149], v[198:201], v[84:87]
	v_mfma_f32_16x16x32_bf16 v[76:79], v[138:141], v[206:209], v[76:79]
	v_mfma_f32_16x16x32_bf16 v[68:71], v[146:149], v[206:209], v[68:71]
	v_mfma_f32_16x16x32_bf16 v[126:129], v[142:145], v[180:183], v[126:129]
	v_mfma_f32_16x16x32_bf16 v[118:121], v[156:159], v[180:183], v[118:121]
	v_mfma_f32_16x16x32_bf16 v[110:113], v[142:145], v[194:197], v[110:113]
	v_mfma_f32_16x16x32_bf16 v[102:105], v[156:159], v[194:197], v[102:105]
	v_mfma_f32_16x16x32_bf16 v[92:95], v[142:145], v[202:205], v[92:95]
	v_mfma_f32_16x16x32_bf16 v[84:87], v[156:159], v[202:205], v[84:87]
	v_mfma_f32_16x16x32_bf16 v[76:79], v[142:145], v[210:213], v[76:79]
	v_mfma_f32_16x16x32_bf16 v[68:71], v[156:159], v[210:213], v[68:71]
	v_mfma_f32_16x16x32_bf16 v[122:125], v[160:163], v[176:179], v[122:125]
	v_mfma_f32_16x16x32_bf16 v[114:117], v[168:171], v[176:179], v[114:117]
	v_mfma_f32_16x16x32_bf16 v[106:109], v[160:163], v[190:193], v[106:109]
	v_mfma_f32_16x16x32_bf16 v[98:101], v[168:171], v[190:193], v[98:101]
	v_mfma_f32_16x16x32_bf16 v[88:91], v[160:163], v[198:201], v[88:91]
	v_mfma_f32_16x16x32_bf16 v[80:83], v[168:171], v[198:201], v[80:83]
	v_mfma_f32_16x16x32_bf16 v[72:75], v[160:163], v[206:209], v[72:75]
	v_mfma_f32_16x16x32_bf16 v[64:67], v[168:171], v[206:209], v[64:67]
	v_mfma_f32_16x16x32_bf16 v[122:125], v[164:167], v[180:183], v[122:125]
	v_mfma_f32_16x16x32_bf16 v[114:117], v[172:175], v[180:183], v[114:117]
	v_mfma_f32_16x16x32_bf16 v[106:109], v[164:167], v[194:197], v[106:109]
	v_mfma_f32_16x16x32_bf16 v[98:101], v[172:175], v[194:197], v[98:101]
	v_mfma_f32_16x16x32_bf16 v[88:91], v[164:167], v[202:205], v[88:91]
	v_mfma_f32_16x16x32_bf16 v[80:83], v[172:175], v[202:205], v[80:83]
	v_mfma_f32_16x16x32_bf16 v[72:75], v[164:167], v[210:213], v[72:75]
	v_mfma_f32_16x16x32_bf16 v[64:67], v[172:175], v[210:213], v[64:67]
	s_setprio 0
	s_barrier
	s_add_i32 s18, s35, s47
	s_mov_b32 m0, s18
	ds_read_b128 v[176:179], v155 offset:16384
	ds_read_b128 v[180:183], v155 offset:17408
	ds_read_b128 v[190:193], v155 offset:18432
	ds_read_b128 v[194:197], v155 offset:19456
	ds_read_b128 v[198:201], v155 offset:20480
	ds_read_b128 v[202:205], v155 offset:21504
	ds_read_b128 v[206:209], v155 offset:22528
	ds_read_b128 v[210:213], v155 offset:23552
	global_load_lds_dwordx4 v134, s[44:45]
	s_add_i32 m0, s18, 0x2000
	s_add_u32 s18, s44, 0x40000
	s_addc_u32 s19, s45, 0
	s_add_i32 s35, s49, s47
	global_load_lds_dwordx4 v130, s[44:45]
	s_mov_b32 m0, s35
	s_nop 0
	global_load_lds_dwordx4 v134, s[18:19]
	s_add_i32 m0, s35, 0x2000
	s_nop 0
	global_load_lds_dwordx4 v130, s[18:19]
	s_waitcnt vmcnt(6)
	s_waitcnt lgkmcnt(0)
	s_barrier
	s_setprio 1
	s_waitcnt lgkmcnt(0)
	v_mfma_f32_16x16x32_bf16 v[60:63], v[138:141], v[176:179], v[60:63]
	v_mfma_f32_16x16x32_bf16 v[52:55], v[146:149], v[176:179], v[52:55]
	v_mfma_f32_16x16x32_bf16 v[44:47], v[138:141], v[190:193], v[44:47]
	v_mfma_f32_16x16x32_bf16 v[36:39], v[146:149], v[190:193], v[36:39]
	v_mfma_f32_16x16x32_bf16 v[28:31], v[138:141], v[198:201], v[28:31]
	v_mfma_f32_16x16x32_bf16 v[20:23], v[146:149], v[198:201], v[20:23]
	v_mfma_f32_16x16x32_bf16 v[12:15], v[138:141], v[206:209], v[12:15]
	v_mfma_f32_16x16x32_bf16 v[4:7], v[146:149], v[206:209], v[4:7]
	v_mfma_f32_16x16x32_bf16 v[60:63], v[142:145], v[180:183], v[60:63]
	v_mfma_f32_16x16x32_bf16 v[52:55], v[156:159], v[180:183], v[52:55]
	v_mfma_f32_16x16x32_bf16 v[44:47], v[142:145], v[194:197], v[44:47]
	v_mfma_f32_16x16x32_bf16 v[36:39], v[156:159], v[194:197], v[36:39]
	v_mfma_f32_16x16x32_bf16 v[28:31], v[142:145], v[202:205], v[28:31]
	v_mfma_f32_16x16x32_bf16 v[20:23], v[156:159], v[202:205], v[20:23]
	v_mfma_f32_16x16x32_bf16 v[12:15], v[142:145], v[210:213], v[12:15]
	v_mfma_f32_16x16x32_bf16 v[4:7], v[156:159], v[210:213], v[4:7]
	v_mfma_f32_16x16x32_bf16 v[56:59], v[160:163], v[176:179], v[56:59]
	v_mfma_f32_16x16x32_bf16 v[48:51], v[168:171], v[176:179], v[48:51]
	v_mfma_f32_16x16x32_bf16 v[40:43], v[160:163], v[190:193], v[40:43]
	v_mfma_f32_16x16x32_bf16 v[32:35], v[168:171], v[190:193], v[32:35]
	v_mfma_f32_16x16x32_bf16 v[24:27], v[160:163], v[198:201], v[24:27]
	v_mfma_f32_16x16x32_bf16 v[16:19], v[168:171], v[198:201], v[16:19]
	v_mfma_f32_16x16x32_bf16 v[8:11], v[160:163], v[206:209], v[8:11]
	v_mfma_f32_16x16x32_bf16 v[0:3], v[168:171], v[206:209], v[0:3]
	v_mfma_f32_16x16x32_bf16 v[56:59], v[164:167], v[180:183], v[56:59]
	v_mfma_f32_16x16x32_bf16 v[48:51], v[172:175], v[180:183], v[48:51]
	v_mfma_f32_16x16x32_bf16 v[40:43], v[164:167], v[194:197], v[40:43]
	v_mfma_f32_16x16x32_bf16 v[32:35], v[172:175], v[194:197], v[32:35]
	v_mfma_f32_16x16x32_bf16 v[24:27], v[164:167], v[202:205], v[24:27]
	v_mfma_f32_16x16x32_bf16 v[16:19], v[172:175], v[202:205], v[16:19]
	v_mfma_f32_16x16x32_bf16 v[8:11], v[164:167], v[210:213], v[8:11]
	v_mfma_f32_16x16x32_bf16 v[0:3], v[172:175], v[210:213], v[0:3]
	s_setprio 0
	s_barrier
	s_add_i32 s35, 0, 0x18000
	v_add_u32_e32 v96, s35, v151
	s_add_i32 s44, 0, 0x1c000
	ds_read_b128 v[138:141], v96
	ds_read_b128 v[142:145], v96 offset:1024
	ds_read_b128 v[146:149], v96 offset:2048
	ds_read_b128 v[156:159], v96 offset:3072
	v_add_u32_e32 v96, s44, v151
	ds_read_b128 v[160:163], v96
	ds_read_b128 v[164:167], v96 offset:1024
	ds_read_b128 v[168:171], v96 offset:2048
	ds_read_b128 v[172:175], v96 offset:3072
	s_mov_b32 m0, s65
	s_nop 0
	global_load_lds_dwordx4 v136, s[42:43]
	s_mov_b32 m0, s72
	s_nop 0
	global_load_lds_dwordx4 v132, s[42:43]
	s_add_u32 s18, s42, 0x40000
	s_addc_u32 s19, s43, 0
	s_mov_b32 m0, s73
	ds_read_b128 v[176:179], v155 offset:32768
	ds_read_b128 v[180:183], v155 offset:33792
	ds_read_b128 v[190:193], v155 offset:34816
	ds_read_b128 v[194:197], v155 offset:35840
	ds_read_b128 v[198:201], v155 offset:36864
	ds_read_b128 v[202:205], v155 offset:37888
	ds_read_b128 v[206:209], v155 offset:38912
	ds_read_b128 v[210:213], v155 offset:39936
	global_load_lds_dwordx4 v136, s[18:19]
	s_mov_b32 m0, s74
	s_nop 0
	global_load_lds_dwordx4 v132, s[18:19]
	s_waitcnt vmcnt(8)
	s_waitcnt lgkmcnt(0)
	s_barrier
	s_setprio 1
	s_waitcnt lgkmcnt(0)
	v_mfma_f32_16x16x32_bf16 v[126:129], v[138:141], v[176:179], v[126:129]
	v_mfma_f32_16x16x32_bf16 v[118:121], v[146:149], v[176:179], v[118:121]
	v_mfma_f32_16x16x32_bf16 v[110:113], v[138:141], v[190:193], v[110:113]
	v_mfma_f32_16x16x32_bf16 v[102:105], v[146:149], v[190:193], v[102:105]
	v_mfma_f32_16x16x32_bf16 v[92:95], v[138:141], v[198:201], v[92:95]
	v_mfma_f32_16x16x32_bf16 v[84:87], v[146:149], v[198:201], v[84:87]
	v_mfma_f32_16x16x32_bf16 v[76:79], v[138:141], v[206:209], v[76:79]
	v_mfma_f32_16x16x32_bf16 v[68:71], v[146:149], v[206:209], v[68:71]
	v_mfma_f32_16x16x32_bf16 v[126:129], v[142:145], v[180:183], v[126:129]
	v_mfma_f32_16x16x32_bf16 v[118:121], v[156:159], v[180:183], v[118:121]
	v_mfma_f32_16x16x32_bf16 v[110:113], v[142:145], v[194:197], v[110:113]
	v_mfma_f32_16x16x32_bf16 v[102:105], v[156:159], v[194:197], v[102:105]
	v_mfma_f32_16x16x32_bf16 v[92:95], v[142:145], v[202:205], v[92:95]
	v_mfma_f32_16x16x32_bf16 v[84:87], v[156:159], v[202:205], v[84:87]
	v_mfma_f32_16x16x32_bf16 v[76:79], v[142:145], v[210:213], v[76:79]
	v_mfma_f32_16x16x32_bf16 v[68:71], v[156:159], v[210:213], v[68:71]
	v_mfma_f32_16x16x32_bf16 v[122:125], v[160:163], v[176:179], v[122:125]
	v_mfma_f32_16x16x32_bf16 v[114:117], v[168:171], v[176:179], v[114:117]
	v_mfma_f32_16x16x32_bf16 v[106:109], v[160:163], v[190:193], v[106:109]
	v_mfma_f32_16x16x32_bf16 v[98:101], v[168:171], v[190:193], v[98:101]
	v_mfma_f32_16x16x32_bf16 v[88:91], v[160:163], v[198:201], v[88:91]
	v_mfma_f32_16x16x32_bf16 v[80:83], v[168:171], v[198:201], v[80:83]
	v_mfma_f32_16x16x32_bf16 v[72:75], v[160:163], v[206:209], v[72:75]
	v_mfma_f32_16x16x32_bf16 v[64:67], v[168:171], v[206:209], v[64:67]
	v_mfma_f32_16x16x32_bf16 v[122:125], v[164:167], v[180:183], v[122:125]
	v_mfma_f32_16x16x32_bf16 v[114:117], v[172:175], v[180:183], v[114:117]
	v_mfma_f32_16x16x32_bf16 v[106:109], v[164:167], v[194:197], v[106:109]
	v_mfma_f32_16x16x32_bf16 v[98:101], v[172:175], v[194:197], v[98:101]
	v_mfma_f32_16x16x32_bf16 v[88:91], v[164:167], v[202:205], v[88:91]
	v_mfma_f32_16x16x32_bf16 v[80:83], v[172:175], v[202:205], v[80:83]
	v_mfma_f32_16x16x32_bf16 v[72:75], v[164:167], v[210:213], v[72:75]
	v_mfma_f32_16x16x32_bf16 v[64:67], v[172:175], v[210:213], v[64:67]
	s_setprio 0
	s_barrier
	s_add_i32 s18, s35, s47
	s_mov_b32 m0, s18
	ds_read_b128 v[176:179], v155 offset:49152
	ds_read_b128 v[180:183], v155 offset:50176
	ds_read_b128 v[190:193], v155 offset:51200
	ds_read_b128 v[194:197], v155 offset:52224
	ds_read_b128 v[198:201], v155 offset:53248
	ds_read_b128 v[202:205], v155 offset:54272
	ds_read_b128 v[206:209], v155 offset:55296
	ds_read_b128 v[210:213], v155 offset:56320
	global_load_lds_dwordx4 v134, s[68:69]
	s_add_i32 m0, s18, 0x2000
	s_add_u32 s18, s68, 0x40000
	s_addc_u32 s19, s69, 0
	s_add_i32 s35, s44, s47
	global_load_lds_dwordx4 v130, s[68:69]
	s_mov_b32 m0, s35
	s_nop 0
	global_load_lds_dwordx4 v134, s[18:19]
	s_add_i32 m0, s35, 0x2000
	s_nop 0
	global_load_lds_dwordx4 v130, s[18:19]
	s_waitcnt vmcnt(6)
	s_cmp_lg_u32 s85, 12
	s_cbranch_scc1 .Lswi_ssq_skip
	global_load_dwordx4 v[220:223], v[252:253], off
	global_load_dwordx4 v[224:227], v[252:253], off offset:1024
	global_load_dwordx4 v[228:231], v[252:253], off offset:2048
	global_load_dwordx4 v[232:235], v[252:253], off offset:3072
	global_load_dwordx4 v[236:239], v[184:185], off
	global_load_dwordx4 v[240:243], v[184:185], off offset:1024
	global_load_dwordx4 v[244:247], v[184:185], off offset:2048
	global_load_dwordx4 v[248:251], v[184:185], off offset:3072
